# layer 0's ffn2-down weight conversion deferred from step 1 to the idle last round of layer 0's first gate/up GEMM (conversion path made layer-generic); step-1 converters do 6 trips
# speedup vs baseline: 1.0019x; 1.0019x over previous
; __device__ __forceinline__ void convert_layer(PP P, int l, LAS unsigned char* lds, const Ids I) {
;     ...
;     for (int u = BID; u < 7 * 176 + 64; u += NB) {
;         const int mi = u / 176, uu = u - mi * 176;
;         if (mi == 0)      conv_tile4(P->in[I_F1G] + wl, 1024, 2816, (bf16_t*)(ws + WS_WGU1), 5, uu, T, I);
;         else if (mi == 1) conv_tile4(P->in[I_F1U] + wl, 1024, 2816, (bf16_t*)(ws + WS_WGU1), 6, uu, T, I);
;         else if (mi == 2) conv_tile4(P->in[I_F1D] + wl, 2816, 1024, (bf16_t*)(ws + WS_WD1), 0, uu, T, I);
;         else if (mi == 3) conv_tile4(P->in[I_WIN] + wl, 1024, 2816, (bf16_t*)(ws + WS_WIN), 4, uu, T, I);
;         else if (mi == 4) conv_tile4(P->in[I_F2G] + wl, 1024, 2816, (bf16_t*)(ws + WS_WGU2), 5, uu, T, I);
;         else if (mi == 5) conv_tile4(P->in[I_F2U] + wl, 1024, 2816, (bf16_t*)(ws + WS_WGU2), 6, uu, T, I);
;         else if (mi == 6) conv_tile4(P->in[I_F2D] + wl, 2816, 1024, (bf16_t*)(ws + WS_WD2), 0, uu, T, I);
;         else              conv_tile4(P->in[I_WOUT] + (size_t)l * 1024 * 1024, 1024, 1024, (bf16_t*)(ws + WS_WOUT), 0, uu, T, I);
;     }
; __global__ void __launch_bounds__(512) mega(Params Pval) {
;     ...
;             } else if (sub == 1 || sub == 10) {
;                 EpiSwiGLU E{(bf16_t*)(ws + WS_R1)}; run_gemm(lds, (const bf16_t*)(ws + WS_HB), (const bf16_t*)(ws + (sub == 1 ? WS_WGU1 : WS_WGU2)), MT, 2 * FF, 1024, E, I);
.LBB0_412:
	v_readlane_b32 s30, v254, 45
	s_mov_b32 s25, s45
	v_readlane_b32 s27, v254, 47
	s_barrier
	s_cmp_eq_u32 s33, 15
	s_cbranch_scc1 .Lcv_c15
	s_cmp_eq_u32 s33, 3
	s_cbranch_scc1 .Lcv_c3
	s_cmp_eq_u32 s33, 12
	s_cbranch_scc0 .LBB0_413
	s_sub_i32 s6, s93, 0xac
	s_cmp_lt_u32 s6, 64
	s_cbranch_scc0 .LBB0_413
	s_mov_b64 s[28:29], s[12:13]
	s_add_i32 s22, s93, 0x424
	s_add_i32 s3, s93, 4
	s_movk_i32 s100, 0x100
	s_mov_b64 s[26:27], 0xb00000
	s_branch .LBB0_504
.Lcv_c3:
	s_cmpk_lt_u32 s93, 0xac
	s_cbranch_scc1 .LBB0_413
	s_mov_b64 s[28:29], s[12:13]
	s_add_i32 s22, s93, 0x374
	s_add_i32 s3, s93, 0xffffff54
	s_movk_i32 s100, 0x54
	s_mov_b64 s[26:27], 0
	s_branch .LBB0_504

; __device__ __forceinline__ void convert_layer(PP P, int l, LAS unsigned char* lds, const Ids I) {
;     ...
;     for (int u = BID; u < 7 * 176 + 64; u += NB) {
;         const int mi = u / 176, uu = u - mi * 176;
;         if (mi == 0)      conv_tile4(P->in[I_F1G] + wl, 1024, 2816, (bf16_t*)(ws + WS_WGU1), 5, uu, T, I);
;         else if (mi == 1) conv_tile4(P->in[I_F1U] + wl, 1024, 2816, (bf16_t*)(ws + WS_WGU1), 6, uu, T, I);
;         else if (mi == 2) conv_tile4(P->in[I_F1D] + wl, 2816, 1024, (bf16_t*)(ws + WS_WD1), 0, uu, T, I);
;         else if (mi == 3) conv_tile4(P->in[I_WIN] + wl, 1024, 2816, (bf16_t*)(ws + WS_WIN), 4, uu, T, I);
;         else if (mi == 4) conv_tile4(P->in[I_F2G] + wl, 1024, 2816, (bf16_t*)(ws + WS_WGU2), 5, uu, T, I);
;         else if (mi == 5) conv_tile4(P->in[I_F2U] + wl, 1024, 2816, (bf16_t*)(ws + WS_WGU2), 6, uu, T, I);
;         else if (mi == 6) conv_tile4(P->in[I_F2D] + wl, 2816, 1024, (bf16_t*)(ws + WS_WD2), 0, uu, T, I);
;         else              conv_tile4(P->in[I_WOUT] + (size_t)l * 1024 * 1024, 1024, 1024, (bf16_t*)(ws + WS_WOUT), 0, uu, T, I);
;     }
.Lcv_exit:
	s_cmp_eq_u32 s33, 15
	s_cbranch_scc1 .Lcv_ret1
	s_cmp_eq_u32 s33, 3
	s_cbranch_scc1 .Lcv_ret1
	s_cmp_eq_u32 s33, 12
	s_cbranch_scc1 .Lcv_ret1
	s_branch .Lcv_ret2

; #define LAS __attribute__((address_space(3)))
; __device__ __forceinline__ int make_tid(int wv) { int lane_v; asm volatile("v_mbcnt_lo_u32_b32 %0, -1, 0\n\tv_mbcnt_hi_u32_b32 %0, -1, %0" : "=v"(lane_v)); return wv * 64 + lane_v; }
; __device__ __forceinline__ unsigned cvt_pk_bf16(float lo, float hi) { unsigned r; asm("v_cvt_pk_bf16_f32 %0, %1, %2" : "=v"(r) : "v"(lo), "v"(hi)); return r; }
; __device__ __forceinline__ void conv_tile4(const float* __restrict__ src, int K, int N, bf16_t* __restrict__ dst, int mode, int u4, LAS float* T, const Ids I) {
;     const int tid_local = make_tid(I.wv);
;     const int tid = TID; const int tilesN = N >> 6;
;     f32x4 v[4][2];
; #pragma unroll
;     for (int q = 0; q < 4; ++q) { const int u = u4 * 4 + q, tk = u / tilesN, tn = u - tk * tilesN;
; #pragma unroll
;         for (int i = 0; i < 2; ++i) { const int kk = (tid >> 4) + 32 * i, n4 = (tid & 15) * 4; v[q][i] = *(const f32x4*)(src + (size_t)(tk * 64 + kk) * N + tn * 64 + n4); } }
; #pragma unroll
;     for (int q = 0; q < 4; ++q)
; #pragma unroll
;         for (int i = 0; i < 2; ++i) { const int kk = (tid >> 4) + 32 * i, n4 = (tid & 15) * 4; LAS float* Tq = T + q * (64 * 65);
;             Tq[(n4 + 0) * 65 + kk] = v[q][i][0]; Tq[(n4 + 1) * 65 + kk] = v[q][i][1]; Tq[(n4 + 2) * 65 + kk] = v[q][i][2]; Tq[(n4 + 3) * 65 + kk] = v[q][i][3]; }
;     __syncthreads();
; #pragma unroll
;     for (int q = 0; q < 4; ++q) { const int u = u4 * 4 + q, tk = u / tilesN, tn = u - tk * tilesN;
;         const int n = tid >> 3, k8 = (tid & 7) * 8; const int ng = tn * 64 + n; const int m3 = mode & 3; int dr = (m3 == 0) ? ng : (((ng >> 7) << 8) + (m3 == 2 ? 128 : 0) + (ng & 127));
;         if (mode & 4) { const int c = dr & 31; dr = (dr & ~31) + 16 * ((c >> 2) & 1) + 4 * (c >> 3) + (c & 3); }
;         const LAS float* tp = T + q * (64 * 65) + n * 65 + k8;
;         u32x4 w; w.x = cvt_pk_bf16(tp[0], tp[1]); w.y = cvt_pk_bf16(tp[2], tp[3]); w.z = cvt_pk_bf16(tp[4], tp[5]); w.w = cvt_pk_bf16(tp[6], tp[7]);
;         *(u32x4*)(dst + (size_t)dr * K + tk * 64 + k8) = w; }
;     __syncthreads();
.LBB0_512:
	s_andn2_b64 vcc, exec, s[6:7]
	s_cbranch_vccnz .LBB0_514
	s_load_dwordx2 s[6:7], s[88:89], 0x130
	v_mbcnt_lo_u32_b32 v32, -1, 0
	v_mbcnt_hi_u32_b32 v32, -1, v32
	s_waitcnt lgkmcnt(0)
	s_lshr_b32 s10, s23, 2
	v_lshlrev_b32_e32 v0, 2, v32
	v_add_u32_e32 v33, s62, v32
	v_and_b32_e32 v35, 60, v0
	s_lshl_b32 s11, s23, 8
	v_ashrrev_i32_e32 v34, 4, v33
	v_lshlrev_b32_e32 v144, 2, v35
	s_lshl_b32 s12, s10, 10
	v_lshl_add_u64 v[0:1], s[6:7], 0, v[144:145]
	v_lshl_add_u32 v2, s10, 6, v34
	s_sub_i32 s6, s11, s12
	s_ashr_i32 s7, s6, 31
	v_ashrrev_i32_e32 v3, 31, v2
	v_lshl_add_u64 v[0:1], s[6:7], 2, v[0:1]
	v_lshlrev_b64 v[2:3], 12, v[2:3]
	v_lshl_add_u64 v[4:5], v[0:1], 0, v[2:3]
	s_mov_b32 s7, s26
	v_add_co_u32_e32 v0, vcc, s7, v4
	s_add_u32 s8, s26, 0x20000
	s_addc_u32 s9, s27, 0
	v_addc_co_u32_e32 v1, vcc, 0, v5, vcc
	s_mov_b32 s7, s8
	v_lshl_add_u64 v[24:25], v[4:5], 0, s[26:27]
	v_lshl_add_u64 v[28:29], v[4:5], 0, s[8:9]
	v_add_co_u32_e32 v4, vcc, s7, v4
	global_load_dwordx4 v[0:3], v[0:1], off
	s_nop 0
	v_addc_co_u32_e32 v5, vcc, 0, v5, vcc
	global_load_dwordx4 v[4:7], v[4:5], off
	s_nop 0
	global_load_dwordx4 v[8:11], v[24:25], off offset:256
	global_load_dwordx4 v[12:15], v[28:29], off offset:256
	global_load_dwordx4 v[16:19], v[24:25], off offset:512
	global_load_dwordx4 v[20:23], v[28:29], off offset:512
	s_nop 0
	global_load_dwordx4 v[24:27], v[24:25], off offset:768
	s_nop 0
	global_load_dwordx4 v[28:31], v[28:29], off offset:768
	v_mul_u32_u24_e32 v35, 0x104, v35
	v_lshlrev_b32_e32 v34, 2, v34
	v_add3_u32 v34, 0, v35, v34
	s_or_b32 s7, s11, 64
	s_sub_i32 s9, s7, s12
	s_or_b32 s7, s11, 0x80
	s_sub_i32 s8, s7, s12
	s_or_b32 s7, s11, 0xc0
	s_sub_i32 s7, s7, s12
	v_readlane_b32 s12, v254, 20
	v_readlane_b32 s13, v254, 21
	s_lshl_b32 s54, s10, 7
	s_waitcnt vmcnt(0)
	ds_write2_b32 v34, v0, v4 offset1:32
	ds_write2_b32 v34, v1, v5 offset0:65 offset1:97
	ds_write2_b32 v34, v2, v6 offset0:130 offset1:162
	ds_write2_b32 v34, v3, v7 offset0:195 offset1:227
	v_add_u32_e32 v0, 0x4000, v34
	ds_write2_b32 v0, v8, v12 offset0:64 offset1:96
	ds_write2_b32 v0, v9, v13 offset0:129 offset1:161
	ds_write2_b32 v0, v10, v14 offset0:194 offset1:226
	v_add_u32_e32 v0, 0x4400, v34
	ds_write2_b32 v0, v11, v15 offset0:3 offset1:35
	v_add_u32_e32 v0, 0x8000, v34
	ds_write2_b32 v0, v16, v20 offset0:128 offset1:160
	ds_write2_b32 v0, v17, v21 offset0:193 offset1:225
	v_add_u32_e32 v0, 0x8400, v34
	ds_write2_b32 v0, v18, v22 offset0:2 offset1:34
	ds_write2_b32 v0, v19, v23 offset0:67 offset1:99
	v_add_u32_e32 v0, 0xc000, v34
	ds_write2_b32 v0, v24, v28 offset0:192 offset1:224
	v_add_u32_e32 v0, 0xc400, v34
	ds_write2_b32 v0, v25, v29 offset0:1 offset1:33
	ds_write2_b32 v0, v26, v30 offset0:66 offset1:98
	ds_write2_b32 v0, v27, v31 offset0:131 offset1:163
	v_lshlrev_b32_e32 v0, 3, v32
	v_ashrrev_i32_e32 v7, 3, v33
	v_and_b32_e32 v10, 56, v0
	v_mul_lo_u32 v0, v7, s66
	v_lshlrev_b32_e32 v1, 2, v10
	v_add3_u32 v6, 0, v0, v1
	s_waitcnt lgkmcnt(0)
	s_barrier
	ds_read2_b32 v[0:1], v6 offset1:1
	ds_read2_b32 v[2:3], v6 offset0:2 offset1:3
	ds_read2_b32 v[4:5], v6 offset0:6 offset1:7
	s_waitcnt lgkmcnt(2)
	v_cvt_pk_bf16_f32 v0, v0, v1
	s_waitcnt lgkmcnt(1)
	v_cvt_pk_bf16_f32 v1, v2, v3
	ds_read2_b32 v[2:3], v6 offset0:4 offset1:5
	v_add_u32_e32 v8, s6, v7
	s_waitcnt lgkmcnt(0)
	v_cvt_pk_bf16_f32 v2, v2, v3
	v_cvt_pk_bf16_f32 v3, v4, v5
	v_mov_b64_e32 v[4:5], s[12:13]
	v_mad_i64_i32 v[8:9], s[12:13], v8, s73, v[4:5]
	v_lshl_add_u64 v[8:9], v[8:9], 0, s[54:55]
	v_lshlrev_b32_e32 v144, 1, v10
	v_lshl_add_u64 v[8:9], v[8:9], 0, v[144:145]
	global_store_dwordx4 v[8:9], v[0:3], off
	v_add_u32_e32 v10, s9, v7
	s_nop 0
	v_add_u32_e32 v0, 0x4100, v6
	ds_read2_b32 v[0:1], v0 offset1:1
	s_waitcnt lgkmcnt(0)
	v_cvt_pk_bf16_f32 v0, v0, v1
	v_add_u32_e32 v1, 0x4108, v6
	ds_read2_b32 v[2:3], v1 offset1:1
	s_waitcnt lgkmcnt(0)
	v_cvt_pk_bf16_f32 v1, v2, v3
	v_add_u32_e32 v2, 0x4110, v6
	ds_read2_b32 v[2:3], v2 offset1:1
	s_waitcnt lgkmcnt(0)
	v_cvt_pk_bf16_f32 v2, v2, v3
	v_add_u32_e32 v3, 0x4118, v6
	ds_read2_b32 v[8:9], v3 offset1:1
	s_waitcnt lgkmcnt(0)
	v_cvt_pk_bf16_f32 v3, v8, v9
	v_mad_i64_i32 v[8:9], s[10:11], v10, s73, v[4:5]
	v_lshl_add_u64 v[8:9], v[8:9], 0, s[54:55]
	v_lshl_add_u64 v[8:9], v[8:9], 0, v[144:145]
	global_store_dwordx4 v[8:9], v[0:3], off
	v_add_u32_e32 v10, s8, v7
	s_nop 0
	v_add_u32_e32 v0, 0x8200, v6
	ds_read2_b32 v[0:1], v0 offset1:1
	s_waitcnt lgkmcnt(0)
	v_cvt_pk_bf16_f32 v0, v0, v1
	v_add_u32_e32 v1, 0x8208, v6
	ds_read2_b32 v[2:3], v1 offset1:1
	s_waitcnt lgkmcnt(0)
	v_cvt_pk_bf16_f32 v1, v2, v3
	v_add_u32_e32 v2, 0x8210, v6
	ds_read2_b32 v[2:3], v2 offset1:1
	s_waitcnt lgkmcnt(0)
	v_cvt_pk_bf16_f32 v2, v2, v3
	v_add_u32_e32 v3, 0x8218, v6
	ds_read2_b32 v[8:9], v3 offset1:1
	s_waitcnt lgkmcnt(0)
	v_cvt_pk_bf16_f32 v3, v8, v9
	v_mad_i64_i32 v[8:9], s[8:9], v10, s73, v[4:5]
	v_lshl_add_u64 v[8:9], v[8:9], 0, s[54:55]
	v_lshl_add_u64 v[8:9], v[8:9], 0, v[144:145]
	global_store_dwordx4 v[8:9], v[0:3], off
	v_add_u32_e32 v8, s7, v7
	v_mad_i64_i32 v[4:5], s[6:7], v8, s73, v[4:5]
	v_add_u32_e32 v0, 0xc300, v6
	ds_read2_b32 v[0:1], v0 offset1:1
	s_waitcnt lgkmcnt(0)
	v_cvt_pk_bf16_f32 v0, v0, v1
	v_add_u32_e32 v1, 0xc308, v6
	ds_read2_b32 v[2:3], v1 offset1:1
	s_waitcnt lgkmcnt(0)
	v_cvt_pk_bf16_f32 v1, v2, v3
	v_add_u32_e32 v2, 0xc310, v6
	ds_read2_b32 v[2:3], v2 offset1:1
	v_lshl_add_u64 v[4:5], v[4:5], 0, s[54:55]
	s_waitcnt lgkmcnt(0)
	v_cvt_pk_bf16_f32 v2, v2, v3
	v_add_u32_e32 v3, 0xc318, v6
	v_lshl_add_u64 v[4:5], v[4:5], 0, v[144:145]
	ds_read2_b32 v[6:7], v3 offset1:1
	s_waitcnt lgkmcnt(0)
	v_cvt_pk_bf16_f32 v3, v6, v7
	global_store_dwordx4 v[4:5], v[0:3], off
	s_barrier

; __device__ __forceinline__ void convert_layer(PP P, int l, LAS unsigned char* lds, const Ids I) {
;     ...
;     for (int u = BID; u < 7 * 176 + 64; u += NB) {
;         const int mi = u / 176, uu = u - mi * 176;
;         if (mi == 0)      conv_tile4(P->in[I_F1G] + wl, 1024, 2816, (bf16_t*)(ws + WS_WGU1), 5, uu, T, I);
;         else if (mi == 1) conv_tile4(P->in[I_F1U] + wl, 1024, 2816, (bf16_t*)(ws + WS_WGU1), 6, uu, T, I);
;         else if (mi == 2) conv_tile4(P->in[I_F1D] + wl, 2816, 1024, (bf16_t*)(ws + WS_WD1), 0, uu, T, I);
;         else if (mi == 3) conv_tile4(P->in[I_WIN] + wl, 1024, 2816, (bf16_t*)(ws + WS_WIN), 4, uu, T, I);
;         else if (mi == 4) conv_tile4(P->in[I_F2G] + wl, 1024, 2816, (bf16_t*)(ws + WS_WGU2), 5, uu, T, I);
;         else if (mi == 5) conv_tile4(P->in[I_F2U] + wl, 1024, 2816, (bf16_t*)(ws + WS_WGU2), 6, uu, T, I);
;         else if (mi == 6) conv_tile4(P->in[I_F2D] + wl, 2816, 1024, (bf16_t*)(ws + WS_WD2), 0, uu, T, I);
;         else              conv_tile4(P->in[I_WOUT] + (size_t)l * 1024 * 1024, 1024, 1024, (bf16_t*)(ws + WS_WOUT), 0, uu, T, I);
;     }
.LBB0_658:
	s_add_i32 s16, s17, s16
	s_sub_i32 s18, s16, 0x420
	s_cmp_lt_i32 s18, 0
	s_cbranch_scc1 .Lcv1_a
	s_add_i32 s18, s18, 0xb0
.Lcv1_a:
	s_cmpk_gt_i32 s16, 0x44f
	s_waitcnt lgkmcnt(0)
	s_cbranch_scc1 .LBB0_687

; __device__ __forceinline__ void convert_layer(PP P, int l, LAS unsigned char* lds, const Ids I) {
;     ...
;     for (int u = BID; u < 7 * 176 + 64; u += NB) {
;         const int mi = u / 176, uu = u - mi * 176;
;         if (mi == 0)      conv_tile4(P->in[I_F1G] + wl, 1024, 2816, (bf16_t*)(ws + WS_WGU1), 5, uu, T, I);
;         else if (mi == 1) conv_tile4(P->in[I_F1U] + wl, 1024, 2816, (bf16_t*)(ws + WS_WGU1), 6, uu, T, I);
;         else if (mi == 2) conv_tile4(P->in[I_F1D] + wl, 2816, 1024, (bf16_t*)(ws + WS_WD1), 0, uu, T, I);
;         else if (mi == 3) conv_tile4(P->in[I_WIN] + wl, 1024, 2816, (bf16_t*)(ws + WS_WIN), 4, uu, T, I);
;         else if (mi == 4) conv_tile4(P->in[I_F2G] + wl, 1024, 2816, (bf16_t*)(ws + WS_WGU2), 5, uu, T, I);
;         else if (mi == 5) conv_tile4(P->in[I_F2U] + wl, 1024, 2816, (bf16_t*)(ws + WS_WGU2), 6, uu, T, I);
;         else if (mi == 6) conv_tile4(P->in[I_F2D] + wl, 2816, 1024, (bf16_t*)(ws + WS_WD2), 0, uu, T, I);
;         else              conv_tile4(P->in[I_WOUT] + (size_t)l * 1024 * 1024, 1024, 1024, (bf16_t*)(ws + WS_WOUT), 0, uu, T, I);
;     }
; __global__ void __launch_bounds__(512) mega(Params Pval) {
;     ...
;             if (I.nb > 144) { if (I.bid < 72) { EpiAda E{(float*)(ws + WS_MOD), P->in[I_BADA]}; run_gemm(lds, (const bf16_t*)(ws + WS_AADA), (const bf16_t*)(ws + WS_R2), 256, 2 * 9216, 1024, E, I); }
;                               else { Ids J = I; J.bid = I.bid - 72; J.nb = I.nb - 72; convert_layer(P, 0, lds, J); } }
.LBB0_715:
	s_barrier
	s_cmp_gt_u32 s93, 15
	s_cbranch_scc1 .LBB0_716
	s_add_i32 s16, s93, 0x450
	s_movk_i32 s17, 0x1000
	s_add_i32 s18, s93, 0xe0
	s_add_u32 s48, s86, 0x4000
	s_addc_u32 s49, s87, 0
	s_branch .LBB0_659
